# speedup vs baseline: 1.0047x; 1.0011x over previous
; __device__ __forceinline__ void gemm_phase(LAS unsigned char* lds, const GemmD& g) {
;     ...
;         const bool has_next = unit_get(g, nM, nN, G, cblk, ui + 1, nxt);
;         const char* nA = has_next ? (const char*)g.A + (size_t)nxt.pm * tstep + (size_t)nxt.k0 * kstep : cA; const char* nB = has_next ? (const char*)g.Bt + (size_t)nxt.pn * tstep + (size_t)nxt.k0 * kstep : cB;
;         const int nt = cur.nt;
;         for (int t = 0; t < nt; t += 2) {
;             const bool last = (t == nt - 2);
;     ...
; #pragma unroll
;         for (int a = 0; a < 2; ++a)
; #pragma unroll
;             for (int b = 0; b < 2; ++b)
; #pragma unroll
;                 for (int m = 0; m < 4; ++m)
; #pragma unroll
;                     for (int n = 0; n < 2; ++n) acc[a][b][m][n] = (f32x4){0.f, 0.f, 0.f, 0.f};
;         cur = nxt; cA = nA; cB = nB; ++ui;
.LBB0_144:
	v_lshl_add_u64 v[132:133], v[2:3], 0, s[46:47]
	v_mov_b32_e32 v2, 0
	v_add_u32_e32 v135, -2, v134
	v_lshl_add_u64 v[130:131], v[4:5], 0, s[44:45]
	s_mov_b32 s4, 0
	v_mov_b32_e32 v3, v2
	v_mov_b32_e32 v4, v2
	v_mov_b32_e32 v5, v2
	v_mov_b32_e32 v6, v2
	v_mov_b32_e32 v7, v2
	v_mov_b32_e32 v8, v2
	v_mov_b32_e32 v9, v2
	v_mov_b32_e32 v18, v2
	v_mov_b32_e32 v19, v2
	v_mov_b32_e32 v20, v2
	v_mov_b32_e32 v21, v2
	v_mov_b32_e32 v22, v2
	v_mov_b32_e32 v23, v2
	v_mov_b32_e32 v24, v2
	v_mov_b32_e32 v25, v2
	v_mov_b32_e32 v34, v2
	v_mov_b32_e32 v35, v2
	v_mov_b32_e32 v36, v2
	v_mov_b32_e32 v37, v2
	v_mov_b32_e32 v38, v2
	v_mov_b32_e32 v39, v2
	v_mov_b32_e32 v40, v2
	v_mov_b32_e32 v41, v2
	v_mov_b32_e32 v50, v2
	v_mov_b32_e32 v51, v2
	v_mov_b32_e32 v52, v2
	v_mov_b32_e32 v53, v2
	v_mov_b32_e32 v54, v2
	v_mov_b32_e32 v55, v2
	v_mov_b32_e32 v56, v2
	v_mov_b32_e32 v57, v2
	v_mov_b32_e32 v10, v2
	v_mov_b32_e32 v11, v2
	v_mov_b32_e32 v12, v2
	v_mov_b32_e32 v13, v2
	v_mov_b32_e32 v14, v2
	v_mov_b32_e32 v15, v2
	v_mov_b32_e32 v16, v2
	v_mov_b32_e32 v17, v2
	v_mov_b32_e32 v26, v2
	v_mov_b32_e32 v27, v2
	v_mov_b32_e32 v28, v2
	v_mov_b32_e32 v29, v2
	v_mov_b32_e32 v30, v2
	v_mov_b32_e32 v31, v2
	v_mov_b32_e32 v32, v2
	v_mov_b32_e32 v33, v2
	v_mov_b32_e32 v42, v2
	v_mov_b32_e32 v43, v2
	v_mov_b32_e32 v44, v2
	v_mov_b32_e32 v45, v2
	v_mov_b32_e32 v46, v2
	v_mov_b32_e32 v47, v2
	v_mov_b32_e32 v48, v2
	v_mov_b32_e32 v49, v2
	v_mov_b32_e32 v58, v2
	v_mov_b32_e32 v59, v2
	v_mov_b32_e32 v60, v2
	v_mov_b32_e32 v61, v2
	v_mov_b32_e32 v62, v2
	v_mov_b32_e32 v63, v2
	v_mov_b32_e32 v64, v2
	v_mov_b32_e32 v65, v2
	v_mov_b32_e32 v66, v2
	v_mov_b32_e32 v67, v2
	v_mov_b32_e32 v68, v2
	v_mov_b32_e32 v69, v2
	v_mov_b32_e32 v70, v2
	v_mov_b32_e32 v71, v2
	v_mov_b32_e32 v72, v2
	v_mov_b32_e32 v73, v2
	s_nop 0
	v_mov_b32_e32 v82, v2
	v_mov_b32_e32 v83, v2
	v_mov_b32_e32 v84, v2
	v_mov_b32_e32 v85, v2
	v_mov_b32_e32 v86, v2
	v_mov_b32_e32 v87, v2
	v_mov_b32_e32 v88, v2
	v_mov_b32_e32 v89, v2
	v_mov_b32_e32 v98, v2
	v_mov_b32_e32 v99, v2
	v_mov_b32_e32 v100, v2
	v_mov_b32_e32 v101, v2
	v_mov_b32_e32 v102, v2
	v_mov_b32_e32 v103, v2
	v_mov_b32_e32 v104, v2
	v_mov_b32_e32 v105, v2
	v_mov_b32_e32 v114, v2
	v_mov_b32_e32 v115, v2
	v_mov_b32_e32 v116, v2
	v_mov_b32_e32 v117, v2
	v_mov_b32_e32 v118, v2
	v_mov_b32_e32 v119, v2
	v_mov_b32_e32 v120, v2
	v_mov_b32_e32 v121, v2
	v_mov_b32_e32 v74, v2
	v_mov_b32_e32 v75, v2
	v_mov_b32_e32 v76, v2
	v_mov_b32_e32 v77, v2
	v_mov_b32_e32 v78, v2
	v_mov_b32_e32 v79, v2
	v_mov_b32_e32 v80, v2
	v_mov_b32_e32 v81, v2
	v_mov_b32_e32 v90, v2
	v_mov_b32_e32 v91, v2
	v_mov_b32_e32 v92, v2
	v_mov_b32_e32 v93, v2
	v_mov_b32_e32 v94, v2
	v_mov_b32_e32 v95, v2
	v_mov_b32_e32 v96, v2
	v_mov_b32_e32 v97, v2
	v_mov_b32_e32 v106, v2
	v_mov_b32_e32 v107, v2
	v_mov_b32_e32 v108, v2
	v_mov_b32_e32 v109, v2
	v_mov_b32_e32 v110, v2
	v_mov_b32_e32 v111, v2
	v_mov_b32_e32 v112, v2
	v_mov_b32_e32 v113, v2
	v_mov_b32_e32 v122, v2
	v_mov_b32_e32 v123, v2
	v_mov_b32_e32 v124, v2
	v_mov_b32_e32 v125, v2
	v_mov_b32_e32 v126, v2
	v_mov_b32_e32 v127, v2
	v_mov_b32_e32 v128, v2
	v_mov_b32_e32 v129, v2
